# v52: + FoX tile-skip threshold 2^-64 (was 2^-150): skipped keys contribute < 2^-51 of the row sum, below f32 and ~fp64 resolution
# speedup vs baseline: 1.0325x; 1.0325x over previous
; template <int MODE>
; __device__ __forceinline__ void attn_unit(const Params& P, LAS unsigned char* lds, const int b, const int h, const int qb) {
;     ...
;     { const bf16_t* qp = Qb + (size_t)q * RS + (FOX ? 0 : 64 * mp) + 8 * hh;
; #pragma unroll
;       for (int ks = 0; ks < NQ; ++ks) Qf[ks] = *(const bf16x8*)(qp + 16 * ks); }
;     const int nt = (q0 + ROWS) / 64;
;     int kt0 = 0;
;     const float* Cl = (const float*)(P.ws + WS_C) + (size_t)(b * 8 + h) * S_;
;     if (FOX) {
;         const int kd = q0 / 64; int pred = 0;
;         if (tid < kd) pred = (tab[TAB_AQ2] + Cl[q0] - Cl[tid * 64 + 63] >= -150.0f) ? 1 : 0;
;         kt0 = kd - __syncthreads_count(pred);
; __device__ __forceinline__ void attn_phase(const Params& P, LAS unsigned char* lds) {
;     ...
;         const int u = misc[0];
;         __syncthreads();
;         if (u < 0) break;
;         const int qi = u / QN, v = u % QN;
;         if (v < 256) { const int bh = qi * 4 + (v >> 6), qb = 63 - (v & 63); if (bounded) attn_unit<1>(P, lds, bh >> 3, bh & 7, qb); else attn_unit<2>(P, lds, bh >> 3, bh & 7, qb); }
;         else { const int v2 = v - 256; const int bh = qi * 4 + (v2 >> 5), qb = 31 - (v2 & 31); attn_unit<0>(P, lds, bh >> 3, bh & 7, qb); }
.LBB0_427:
	s_or_b64 exec, exec, s[64:65]
	s_waitcnt lgkmcnt(0)
	s_barrier
	ds_read_b32 v0, v234
	s_waitcnt lgkmcnt(0)
	s_barrier
	v_cmp_gt_i32_e32 vcc, 0, v0
	v_readfirstlane_b32 s0, v0
	s_cbranch_vccnz .LBB0_460
	s_mul_hi_u32 s1, s0, 0xaaaaaaab
	s_lshr_b32 s11, s1, 8
	s_mul_i32 s1, s11, 0x180
	s_sub_i32 s10, s0, s1
	s_cmpk_gt_u32 s10, 0xff
	s_mov_b64 s[8:9], -1
	s_cbranch_scc0 .LBB0_466
	s_add_i32 s0, s10, 0xffffff00
	v_mov_b32_e32 v5, v178
	s_lshl_b32 s1, s11, 2
	s_lshr_b32 s0, s0, 5
	s_add_i32 s12, s0, s1
	v_readfirstlane_b32 s23, v5
	s_andn2_b32 s1, 31, s10
	s_ashr_i32 s22, s23, 6
	s_lshl_b32 s38, s1, 8
	s_lshl_b32 s0, s22, 5
	s_add_i32 s0, s0, s38
	v_and_or_b32 v180, v5, 31, s0
	s_lshl_b64 s[8:9], s[12:13], 21
	s_add_u32 s8, s18, s8
	v_ashrrev_i32_e32 v181, 31, v180
	v_bfe_u32 v4, v5, 5, 1
	s_addc_u32 s9, s19, s9
	v_lshlrev_b64 v[2:3], 8, v[180:181]
	v_lshl_add_u64 v[2:3], s[8:9], 0, v[2:3]
	v_lshlrev_b32_e32 v0, 4, v4
	v_lshl_add_u64 v[2:3], v[2:3], 0, v[0:1]
	global_load_dwordx4 v[130:133], v[2:3], off
	global_load_dwordx4 v[134:137], v[2:3], off offset:32
	global_load_dwordx4 v[138:141], v[2:3], off offset:64
	global_load_dwordx4 v[142:145], v[2:3], off offset:96
	global_load_dwordx4 v[146:149], v[2:3], off offset:128
	global_load_dwordx4 v[150:153], v[2:3], off offset:160
	global_load_dwordx4 v[154:157], v[2:3], off offset:192
	global_load_dwordx4 v[158:161], v[2:3], off offset:224
	s_lshl_b64 s[8:9], s[12:13], 15
	s_add_u32 s66, s82, s8
	s_addc_u32 s67, s83, s9
	v_lshlrev_b32_e32 v207, 2, v180
	global_load_dword v208, v207, s[66:67]
	s_lshl_b32 s33, s1, 2
	v_cmp_gt_i32_e32 vcc, s33, v5
	v_mov_b32_e32 v0, 0
	s_and_saveexec_b64 s[8:9], vcc
	s_cbranch_execz .LBB0_431
	v_lshlrev_b32_e32 v2, 6, v5
	s_lshl_b32 s1, s38, 2
	v_ashrrev_i32_e32 v3, 31, v2
	v_mov_b32_e32 v0, s1
	v_lshl_add_u64 v[2:3], v[2:3], 2, s[66:67]
	global_load_dword v6, v1, s[60:61]
	s_nop 0
	global_load_dword v0, v0, s[66:67]
	s_nop 0
	global_load_dword v2, v[2:3], off offset:252
	s_mov_b32 s1, 0xc2800000
	s_waitcnt vmcnt(1)
	v_add_f32_e32 v0, v6, v0
	s_waitcnt vmcnt(0)
	v_sub_f32_e32 v0, v0, v2
	v_cmp_le_f32_e32 vcc, s1, v0
	s_nop 1
	v_cndmask_b32_e64 v0, 0, 1, vcc
